# v14 + band-attn softmax exponent args as v_pk_fma_f32 and packed pairwise row sums (uniform-bias path); scratch SGPRs moved to s100/s101
# speedup vs baseline: 1.0242x; 1.0005x over previous
.LBB0_723:
	v_lshl_add_u32 v184, s6, 8, v186
	v_lshlrev_b32_e32 v146, 6, v184
	v_mov_b32_e32 v147, 0
	v_lshl_add_u64 v[146:147], v[140:141], 0, v[146:147]
	s_mov_b64 s[100:101], 0x2000
	v_lshl_add_u64 v[148:149], v[146:147], 0, s[100:101]
	global_load_dwordx4 v[206:209], v[146:147], off
	global_load_dwordx4 v[210:213], v[146:147], off offset:1024
	global_load_dwordx4 v[214:217], v[146:147], off offset:2048
	global_load_dwordx4 v[218:221], v[146:147], off offset:3072
	global_load_dwordx4 v[222:225], v[148:149], off
	global_load_dwordx4 v[226:229], v[148:149], off offset:1024
	global_load_dwordx4 v[230:233], v[148:149], off offset:2048
	global_load_dwordx4 v[234:237], v[148:149], off offset:3072
	v_lshl_or_b32 v150, s46, 7, v188
	v_mov_b32_e32 v151, 0
	v_lshlrev_b32_e32 v147, 2, v150
	v_mov_b32_e32 v146, v147
	v_mov_b32_e32 v147, 0
	v_lshl_add_u64 v[148:149], s[30:31], 0, v[146:147]
	global_load_dwordx4 v[168:171], v[148:149], off
	global_load_dwordx4 v[192:195], v[148:149], off offset:16
	v_lshl_add_u64 v[148:149], s[0:1], 0, v[146:147]
	global_load_dwordx4 v[172:175], v[148:149], off
	global_load_dwordx4 v[196:199], v[148:149], off offset:16
	v_lshl_add_u64 v[148:149], s[48:49], 0, v[146:147]
	global_load_dwordx4 v[176:179], v[148:149], off
	global_load_dwordx4 v[200:203], v[148:149], off offset:16
	v_lshl_add_u64 v[148:149], s[82:83], 0, v[146:147]
	global_load_dwordx4 v[180:183], v[148:149], off
	global_load_dwordx4 v[238:241], v[148:149], off offset:16
	v_mul_lo_u32 v185, v184, s67
	v_add_lshl_u32 v185, v185, v150, 1
	s_lshl_b32 s5, s6, 2
	s_add_i32 s5, s5, s80
	s_mul_hi_i32 s7, s5, 0x8400
	s_mul_i32 s5, s5, 0x8400
	s_add_u32 s6, s56, s5
	s_addc_u32 s7, s57, s7
	v_lshl_add_u64 v[246:247], v[150:151], 1, s[6:7]
	v_lshl_add_u64 v[246:247], v[246:247], 0, v[138:139]
	v_xor_b32_e32 v148, 16, v191
	v_xor_b32_e32 v149, 32, v191
	v_lshlrev_b32_e32 v148, 2, v148
	v_lshlrev_b32_e32 v149, 2, v149
	s_mov_b32 s100, 0xbfb8aa3b
	s_waitcnt vmcnt(0)
	v_add_f32_e32 v206, v206, v207
	v_add_f32_e32 v208, v208, v209
	v_add_f32_e32 v210, v210, v211
	v_add_f32_e32 v212, v212, v213
	v_add_f32_e32 v214, v214, v215
	v_add_f32_e32 v216, v216, v217
	v_add_f32_e32 v218, v218, v219
	v_add_f32_e32 v220, v220, v221
	v_add_f32_e32 v222, v222, v223
	v_add_f32_e32 v224, v224, v225
	v_add_f32_e32 v226, v226, v227
	v_add_f32_e32 v228, v228, v229
	v_add_f32_e32 v230, v230, v231
	v_add_f32_e32 v232, v232, v233
	v_add_f32_e32 v234, v234, v235
	v_add_f32_e32 v236, v236, v237
	v_add_f32_e32 v206, v206, v208
	v_add_f32_e32 v210, v210, v212
	v_add_f32_e32 v214, v214, v216
	v_add_f32_e32 v218, v218, v220
	v_add_f32_e32 v222, v222, v224
	v_add_f32_e32 v226, v226, v228
	v_add_f32_e32 v230, v230, v232
	v_add_f32_e32 v234, v234, v236
	ds_bpermute_b32 v207, v148, v206
	ds_bpermute_b32 v211, v148, v210
	ds_bpermute_b32 v215, v148, v214
	ds_bpermute_b32 v219, v148, v218
	ds_bpermute_b32 v223, v148, v222
	ds_bpermute_b32 v227, v148, v226
	ds_bpermute_b32 v231, v148, v230
	ds_bpermute_b32 v235, v148, v234
	s_waitcnt lgkmcnt(0)
	v_add_f32_e32 v206, v206, v207
	v_add_f32_e32 v210, v210, v211
	v_add_f32_e32 v214, v214, v215
	v_add_f32_e32 v218, v218, v219
	v_add_f32_e32 v222, v222, v223
	v_add_f32_e32 v226, v226, v227
	v_add_f32_e32 v230, v230, v231
	v_add_f32_e32 v234, v234, v235
	ds_bpermute_b32 v207, v149, v206
	ds_bpermute_b32 v211, v149, v210
	ds_bpermute_b32 v215, v149, v214
	ds_bpermute_b32 v219, v149, v218
	ds_bpermute_b32 v223, v149, v222
	ds_bpermute_b32 v227, v149, v226
	ds_bpermute_b32 v231, v149, v230
	ds_bpermute_b32 v235, v149, v234
	s_waitcnt lgkmcnt(0)
	v_add_f32_e32 v206, v206, v207
	v_add_f32_e32 v210, v210, v211
	v_add_f32_e32 v214, v214, v215
	v_add_f32_e32 v218, v218, v219
	v_add_f32_e32 v222, v222, v223
	v_add_f32_e32 v226, v226, v227
	v_add_f32_e32 v230, v230, v231
	v_add_f32_e32 v234, v234, v235
	v_pk_mul_f32 v[168:169], v[168:169], s[100:101] op_sel_hi:[1,0]
	v_pk_mul_f32 v[170:171], v[170:171], s[100:101] op_sel_hi:[1,0]
	v_pk_mul_f32 v[172:173], v[172:173], s[100:101] op_sel_hi:[1,0]
	v_pk_mul_f32 v[174:175], v[174:175], s[100:101] op_sel_hi:[1,0]
	v_pk_mul_f32 v[176:177], v[176:177], s[100:101] op_sel_hi:[1,0]
	v_pk_mul_f32 v[178:179], v[178:179], s[100:101] op_sel_hi:[1,0]
	v_pk_mul_f32 v[180:181], v[180:181], s[100:101] op_sel_hi:[1,0]
	v_pk_mul_f32 v[182:183], v[182:183], s[100:101] op_sel_hi:[1,0]
	v_pk_mul_f32 v[192:193], v[192:193], s[100:101] op_sel_hi:[1,0]
	v_pk_mul_f32 v[194:195], v[194:195], s[100:101] op_sel_hi:[1,0]
	v_pk_mul_f32 v[196:197], v[196:197], s[100:101] op_sel_hi:[1,0]
	v_pk_mul_f32 v[198:199], v[198:199], s[100:101] op_sel_hi:[1,0]
	v_pk_mul_f32 v[200:201], v[200:201], s[100:101] op_sel_hi:[1,0]
	v_pk_mul_f32 v[202:203], v[202:203], s[100:101] op_sel_hi:[1,0]
	v_pk_mul_f32 v[238:239], v[238:239], s[100:101] op_sel_hi:[1,0]
	v_pk_mul_f32 v[240:241], v[240:241], s[100:101] op_sel_hi:[1,0]
	v_fmamk_f32 v206, v206, 0x3a800000, v154
	v_cmp_gt_f32_e32 vcc, s84, v206
	v_mul_f32_e32 v207, 0x4b800000, v206
	s_nop 0
	v_cndmask_b32_e32 v206, v206, v207, vcc
	v_rsq_f32_e32 v206, v206
	s_nop 0
	v_mul_f32_e32 v207, 0x45800000, v206
	v_cndmask_b32_e32 v206, v206, v207, vcc
	v_mul_f32_e32 v208, 0xbf317218, v206
	v_fmamk_f32 v210, v210, 0x3a800000, v154
	v_cmp_gt_f32_e32 vcc, s84, v210
	v_mul_f32_e32 v211, 0x4b800000, v210
	s_nop 0
	v_cndmask_b32_e32 v210, v210, v211, vcc
	v_rsq_f32_e32 v210, v210
	s_nop 0
	v_mul_f32_e32 v211, 0x45800000, v210
	v_cndmask_b32_e32 v210, v210, v211, vcc
	v_mul_f32_e32 v212, 0xbf317218, v210
	v_fmamk_f32 v214, v214, 0x3a800000, v154
	v_cmp_gt_f32_e32 vcc, s84, v214
	v_mul_f32_e32 v215, 0x4b800000, v214
	s_nop 0
	v_cndmask_b32_e32 v214, v214, v215, vcc
	v_rsq_f32_e32 v214, v214
	s_nop 0
	v_mul_f32_e32 v215, 0x45800000, v214
	v_cndmask_b32_e32 v214, v214, v215, vcc
	v_mul_f32_e32 v216, 0xbf317218, v214
	v_fmamk_f32 v218, v218, 0x3a800000, v154
	v_cmp_gt_f32_e32 vcc, s84, v218
	v_mul_f32_e32 v219, 0x4b800000, v218
	s_nop 0
	v_cndmask_b32_e32 v218, v218, v219, vcc
	v_rsq_f32_e32 v218, v218
	s_nop 0
	v_mul_f32_e32 v219, 0x45800000, v218
	v_cndmask_b32_e32 v218, v218, v219, vcc
	v_mul_f32_e32 v220, 0xbf317218, v218
	v_fmamk_f32 v222, v222, 0x3a800000, v154
	v_cmp_gt_f32_e32 vcc, s84, v222
	v_mul_f32_e32 v223, 0x4b800000, v222
	s_nop 0
	v_cndmask_b32_e32 v222, v222, v223, vcc
	v_rsq_f32_e32 v222, v222
	s_nop 0
	v_mul_f32_e32 v223, 0x45800000, v222
	v_cndmask_b32_e32 v222, v222, v223, vcc
	v_mul_f32_e32 v224, 0xbf317218, v222
	v_fmamk_f32 v226, v226, 0x3a800000, v154
	v_cmp_gt_f32_e32 vcc, s84, v226
	v_mul_f32_e32 v227, 0x4b800000, v226
	s_nop 0
	v_cndmask_b32_e32 v226, v226, v227, vcc
	v_rsq_f32_e32 v226, v226
	s_nop 0
	v_mul_f32_e32 v227, 0x45800000, v226
	v_cndmask_b32_e32 v226, v226, v227, vcc
	v_mul_f32_e32 v228, 0xbf317218, v226
	v_fmamk_f32 v230, v230, 0x3a800000, v154
	v_cmp_gt_f32_e32 vcc, s84, v230
	v_mul_f32_e32 v231, 0x4b800000, v230
	s_nop 0
	v_cndmask_b32_e32 v230, v230, v231, vcc
	v_rsq_f32_e32 v230, v230
	s_nop 0
	v_mul_f32_e32 v231, 0x45800000, v230
	v_cndmask_b32_e32 v230, v230, v231, vcc
	v_mul_f32_e32 v232, 0xbf317218, v230
	v_fmamk_f32 v234, v234, 0x3a800000, v154
	v_cmp_gt_f32_e32 vcc, s84, v234
	v_mul_f32_e32 v235, 0x4b800000, v234
	s_nop 0
	v_cndmask_b32_e32 v234, v234, v235, vcc
	v_rsq_f32_e32 v234, v234
	s_nop 0
	v_mul_f32_e32 v235, 0x45800000, v234
	v_cndmask_b32_e32 v234, v234, v235, vcc
	v_mul_f32_e32 v236, 0xbf317218, v234
	s_and_saveexec_b64 s[6:7], s[40:41]
	v_pk_mul_f32 v[242:243], v[124:125], v[206:207] op_sel_hi:[1,0]
	v_pk_mul_f32 v[244:245], v[126:127], v[206:207] op_sel_hi:[1,0]
	s_mov_b32 s100, 0x5800
	s_mov_b32 s101, 0
	v_cvt_pk_bf16_f32 v242, v242, v243
	v_cvt_pk_bf16_f32 v243, v244, v245
	v_lshl_add_u64 v[150:151], v[246:247], 0, s[100:101]
	global_store_dwordx2 v[150:151], v[242:243], off
	s_or_b64 exec, exec, s[6:7]
	v_pk_mul_f32 v[128:129], v[128:129], v[206:207] op_sel_hi:[1,0]
	v_pk_mul_f32 v[130:131], v[130:131], v[206:207] op_sel_hi:[1,0]
	v_pk_mul_f32 v[124:125], v[124:125], v[208:209] op_sel_hi:[1,0]
	v_pk_mul_f32 v[126:127], v[126:127], v[208:209] op_sel_hi:[1,0]
	v_pk_fma_f32 v[146:147], v[176:177], v[128:129], v[180:181]
	v_pk_fma_f32 v[148:149], v[178:179], v[130:131], v[182:183]
	v_fmac_f32_dpp v146, v128, v172 row_shr:1 row_mask:0xf bank_mask:0xf bound_ctrl:1
	v_fmac_f32_dpp v147, v129, v173 row_shr:1 row_mask:0xf bank_mask:0xf bound_ctrl:1
	v_fmac_f32_dpp v148, v130, v174 row_shr:1 row_mask:0xf bank_mask:0xf bound_ctrl:1
	v_fmac_f32_dpp v149, v131, v175 row_shr:1 row_mask:0xf bank_mask:0xf bound_ctrl:1
	v_fmac_f32_dpp v146, v128, v168 row_shr:2 row_mask:0xf bank_mask:0xf bound_ctrl:1
	v_fmac_f32_dpp v147, v129, v169 row_shr:2 row_mask:0xf bank_mask:0xf bound_ctrl:1
	v_fmac_f32_dpp v148, v130, v170 row_shr:2 row_mask:0xf bank_mask:0xf bound_ctrl:1
	v_fmac_f32_dpp v149, v131, v171 row_shr:2 row_mask:0xf bank_mask:0xf bound_ctrl:1
	v_exp_f32_e32 v242, v146
	v_exp_f32_e32 v243, v147
	v_exp_f32_e32 v244, v148
	v_exp_f32_e32 v245, v149
	v_pk_mul_f32 v[146:147], v[146:147], v[124:125]
	v_pk_mul_f32 v[148:149], v[148:149], v[126:127]
	v_pk_add_f32 v[242:243], v[242:243], 1.0 op_sel_hi:[1,0]
	v_pk_add_f32 v[244:245], v[244:245], 1.0 op_sel_hi:[1,0]
	v_rcp_f32_e32 v242, v242
	v_rcp_f32_e32 v243, v243
	v_rcp_f32_e32 v244, v244
	v_rcp_f32_e32 v245, v245
	v_cvt_pk_bf16_f32 v126, v128, v129
	v_cvt_pk_bf16_f32 v127, v130, v131
	v_pk_mul_f32 v[146:147], v[146:147], v[242:243]
	v_pk_mul_f32 v[148:149], v[148:149], v[244:245]
	s_mov_b32 s100, 0x2c00
	s_mov_b32 s101, 0
	s_and_saveexec_b64 s[6:7], s[40:41]
	v_lshl_add_u64 v[150:151], v[246:247], 0, s[100:101]
	global_store_dwordx2 v[150:151], v[126:127], off
	s_or_b64 exec, exec, s[6:7]
	v_cvt_pk_bf16_f32 v124, v146, v147
	v_cvt_pk_bf16_f32 v125, v148, v149
	v_pk_mul_f32 v[120:121], v[120:121], v[210:211] op_sel_hi:[1,0]
	v_pk_mul_f32 v[122:123], v[122:123], v[210:211] op_sel_hi:[1,0]
	v_pk_mul_f32 v[116:117], v[116:117], v[212:213] op_sel_hi:[1,0]
	v_pk_mul_f32 v[118:119], v[118:119], v[212:213] op_sel_hi:[1,0]
	v_pk_fma_f32 v[146:147], v[176:177], v[120:121], v[180:181]
	v_pk_fma_f32 v[148:149], v[178:179], v[122:123], v[182:183]
	v_fmac_f32_dpp v146, v120, v172 row_shr:1 row_mask:0xf bank_mask:0xf bound_ctrl:1
	v_fmac_f32_dpp v147, v121, v173 row_shr:1 row_mask:0xf bank_mask:0xf bound_ctrl:1
	v_fmac_f32_dpp v148, v122, v174 row_shr:1 row_mask:0xf bank_mask:0xf bound_ctrl:1
	v_fmac_f32_dpp v149, v123, v175 row_shr:1 row_mask:0xf bank_mask:0xf bound_ctrl:1
	v_fmac_f32_dpp v146, v128, v172 row_shl:15 row_mask:0xf bank_mask:0xf
	v_fmac_f32_dpp v147, v129, v173 row_shl:15 row_mask:0xf bank_mask:0xf
	v_fmac_f32_dpp v148, v130, v174 row_shl:15 row_mask:0xf bank_mask:0xf
	v_fmac_f32_dpp v149, v131, v175 row_shl:15 row_mask:0xf bank_mask:0xf
	v_fmac_f32_dpp v146, v120, v168 row_shr:2 row_mask:0xf bank_mask:0xf bound_ctrl:1
	v_fmac_f32_dpp v147, v121, v169 row_shr:2 row_mask:0xf bank_mask:0xf bound_ctrl:1
	v_fmac_f32_dpp v148, v122, v170 row_shr:2 row_mask:0xf bank_mask:0xf bound_ctrl:1
	v_fmac_f32_dpp v149, v123, v171 row_shr:2 row_mask:0xf bank_mask:0xf bound_ctrl:1
	v_fmac_f32_dpp v146, v128, v168 row_shl:14 row_mask:0xf bank_mask:0xf
	v_fmac_f32_dpp v147, v129, v169 row_shl:14 row_mask:0xf bank_mask:0xf
	v_fmac_f32_dpp v148, v130, v170 row_shl:14 row_mask:0xf bank_mask:0xf
	v_fmac_f32_dpp v149, v131, v171 row_shl:14 row_mask:0xf bank_mask:0xf
	v_exp_f32_e32 v242, v146
	v_exp_f32_e32 v243, v147
	v_exp_f32_e32 v244, v148
	v_exp_f32_e32 v245, v149
	v_pk_mul_f32 v[146:147], v[146:147], v[116:117]
	v_pk_mul_f32 v[148:149], v[148:149], v[118:119]
	v_pk_add_f32 v[242:243], v[242:243], 1.0 op_sel_hi:[1,0]
	v_pk_add_f32 v[244:245], v[244:245], 1.0 op_sel_hi:[1,0]
	v_rcp_f32_e32 v242, v242
	v_rcp_f32_e32 v243, v243
	v_rcp_f32_e32 v244, v244
	v_rcp_f32_e32 v245, v245
	s_nop 0
	v_pk_mul_f32 v[146:147], v[146:147], v[242:243]
	v_pk_mul_f32 v[148:149], v[148:149], v[244:245]
	v_cvt_pk_bf16_f32 v116, v146, v147
	v_cvt_pk_bf16_f32 v117, v148, v149
	v_pk_mul_f32 v[112:113], v[112:113], v[214:215] op_sel_hi:[1,0]
	v_pk_mul_f32 v[114:115], v[114:115], v[214:215] op_sel_hi:[1,0]
	v_pk_mul_f32 v[98:99], v[98:99], v[216:217] op_sel_hi:[1,0]
	v_pk_mul_f32 v[100:101], v[100:101], v[216:217] op_sel_hi:[1,0]
	v_pk_fma_f32 v[146:147], v[176:177], v[112:113], v[180:181]
	v_pk_fma_f32 v[148:149], v[178:179], v[114:115], v[182:183]
	v_fmac_f32_dpp v146, v112, v172 row_shr:1 row_mask:0xf bank_mask:0xf bound_ctrl:1
	v_fmac_f32_dpp v147, v113, v173 row_shr:1 row_mask:0xf bank_mask:0xf bound_ctrl:1
	v_fmac_f32_dpp v148, v114, v174 row_shr:1 row_mask:0xf bank_mask:0xf bound_ctrl:1
	v_fmac_f32_dpp v149, v115, v175 row_shr:1 row_mask:0xf bank_mask:0xf bound_ctrl:1
	v_fmac_f32_dpp v146, v120, v172 row_shl:15 row_mask:0xf bank_mask:0xf
	v_fmac_f32_dpp v147, v121, v173 row_shl:15 row_mask:0xf bank_mask:0xf
	v_fmac_f32_dpp v148, v122, v174 row_shl:15 row_mask:0xf bank_mask:0xf
	v_fmac_f32_dpp v149, v123, v175 row_shl:15 row_mask:0xf bank_mask:0xf
	v_fmac_f32_dpp v146, v112, v168 row_shr:2 row_mask:0xf bank_mask:0xf bound_ctrl:1
	v_fmac_f32_dpp v147, v113, v169 row_shr:2 row_mask:0xf bank_mask:0xf bound_ctrl:1
	v_fmac_f32_dpp v148, v114, v170 row_shr:2 row_mask:0xf bank_mask:0xf bound_ctrl:1
	v_fmac_f32_dpp v149, v115, v171 row_shr:2 row_mask:0xf bank_mask:0xf bound_ctrl:1
	v_fmac_f32_dpp v146, v120, v168 row_shl:14 row_mask:0xf bank_mask:0xf
	v_fmac_f32_dpp v147, v121, v169 row_shl:14 row_mask:0xf bank_mask:0xf
	v_fmac_f32_dpp v148, v122, v170 row_shl:14 row_mask:0xf bank_mask:0xf
	v_fmac_f32_dpp v149, v123, v171 row_shl:14 row_mask:0xf bank_mask:0xf
	v_exp_f32_e32 v242, v146
	v_exp_f32_e32 v243, v147
	v_exp_f32_e32 v244, v148
	v_exp_f32_e32 v245, v149
	v_pk_mul_f32 v[146:147], v[146:147], v[98:99]
	v_pk_mul_f32 v[148:149], v[148:149], v[100:101]
	v_pk_add_f32 v[242:243], v[242:243], 1.0 op_sel_hi:[1,0]
	v_pk_add_f32 v[244:245], v[244:245], 1.0 op_sel_hi:[1,0]
	v_rcp_f32_e32 v242, v242
	v_rcp_f32_e32 v243, v243
	v_rcp_f32_e32 v244, v244
	v_rcp_f32_e32 v245, v245
	s_nop 0
	v_pk_mul_f32 v[146:147], v[146:147], v[242:243]
	v_pk_mul_f32 v[148:149], v[148:149], v[244:245]
	v_cvt_pk_bf16_f32 v98, v146, v147
	v_cvt_pk_bf16_f32 v99, v148, v149
	v_pk_mul_f32 v[108:109], v[108:109], v[218:219] op_sel_hi:[1,0]
	v_pk_mul_f32 v[110:111], v[110:111], v[218:219] op_sel_hi:[1,0]
	v_pk_mul_f32 v[104:105], v[104:105], v[220:221] op_sel_hi:[1,0]
	v_pk_mul_f32 v[106:107], v[106:107], v[220:221] op_sel_hi:[1,0]
	v_pk_fma_f32 v[146:147], v[176:177], v[108:109], v[180:181]
	v_pk_fma_f32 v[148:149], v[178:179], v[110:111], v[182:183]
	v_fmac_f32_dpp v146, v108, v172 row_shr:1 row_mask:0xf bank_mask:0xf bound_ctrl:1
	v_fmac_f32_dpp v147, v109, v173 row_shr:1 row_mask:0xf bank_mask:0xf bound_ctrl:1
	v_fmac_f32_dpp v148, v110, v174 row_shr:1 row_mask:0xf bank_mask:0xf bound_ctrl:1
	v_fmac_f32_dpp v149, v111, v175 row_shr:1 row_mask:0xf bank_mask:0xf bound_ctrl:1
	v_fmac_f32_dpp v146, v112, v172 row_shl:15 row_mask:0xf bank_mask:0xf
	v_fmac_f32_dpp v147, v113, v173 row_shl:15 row_mask:0xf bank_mask:0xf
	v_fmac_f32_dpp v148, v114, v174 row_shl:15 row_mask:0xf bank_mask:0xf
	v_fmac_f32_dpp v149, v115, v175 row_shl:15 row_mask:0xf bank_mask:0xf
	v_fmac_f32_dpp v146, v108, v168 row_shr:2 row_mask:0xf bank_mask:0xf bound_ctrl:1
	v_fmac_f32_dpp v147, v109, v169 row_shr:2 row_mask:0xf bank_mask:0xf bound_ctrl:1
	v_fmac_f32_dpp v148, v110, v170 row_shr:2 row_mask:0xf bank_mask:0xf bound_ctrl:1
	v_fmac_f32_dpp v149, v111, v171 row_shr:2 row_mask:0xf bank_mask:0xf bound_ctrl:1
	v_fmac_f32_dpp v146, v112, v168 row_shl:14 row_mask:0xf bank_mask:0xf
	v_fmac_f32_dpp v147, v113, v169 row_shl:14 row_mask:0xf bank_mask:0xf
	v_fmac_f32_dpp v148, v114, v170 row_shl:14 row_mask:0xf bank_mask:0xf
	v_fmac_f32_dpp v149, v115, v171 row_shl:14 row_mask:0xf bank_mask:0xf
	v_exp_f32_e32 v242, v146
	v_exp_f32_e32 v243, v147
	v_exp_f32_e32 v244, v148
	v_exp_f32_e32 v245, v149
	v_pk_mul_f32 v[146:147], v[146:147], v[104:105]
	v_pk_mul_f32 v[148:149], v[148:149], v[106:107]
	v_pk_add_f32 v[242:243], v[242:243], 1.0 op_sel_hi:[1,0]
	v_pk_add_f32 v[244:245], v[244:245], 1.0 op_sel_hi:[1,0]
	v_rcp_f32_e32 v242, v242
	v_rcp_f32_e32 v243, v243
	v_rcp_f32_e32 v244, v244
	v_rcp_f32_e32 v245, v245
	v_cvt_pk_bf16_f32 v106, v108, v109
	v_cvt_pk_bf16_f32 v107, v110, v111
	v_pk_mul_f32 v[146:147], v[146:147], v[242:243]
	v_pk_mul_f32 v[148:149], v[148:149], v[244:245]
	s_mov_b32 s100, 0xfffecc00
	s_mov_b32 s101, -1
	s_and_saveexec_b64 s[6:7], s[42:43]
	v_lshl_add_u64 v[150:151], v[246:247], 0, s[100:101]
	global_store_dwordx2 v[150:151], v[106:107], off
	s_or_b64 exec, exec, s[6:7]
	v_cvt_pk_bf16_f32 v104, v146, v147
	v_cvt_pk_bf16_f32 v105, v148, v149
	s_and_saveexec_b64 s[6:7], s[40:41]
	v_pk_mul_f32 v[242:243], v[88:89], v[222:223] op_sel_hi:[1,0]
	v_pk_mul_f32 v[244:245], v[90:91], v[222:223] op_sel_hi:[1,0]
	s_mov_b32 s100, 0x16000
	s_mov_b32 s101, 0
	v_cvt_pk_bf16_f32 v242, v242, v243
	v_cvt_pk_bf16_f32 v243, v244, v245
	v_lshl_add_u64 v[150:151], v[246:247], 0, s[100:101]
	global_store_dwordx2 v[150:151], v[242:243], off
	s_or_b64 exec, exec, s[6:7]
	v_pk_mul_f32 v[94:95], v[94:95], v[222:223] op_sel_hi:[1,0]
	v_pk_mul_f32 v[96:97], v[96:97], v[222:223] op_sel_hi:[1,0]
	v_pk_mul_f32 v[88:89], v[88:89], v[224:225] op_sel_hi:[1,0]
	v_pk_mul_f32 v[90:91], v[90:91], v[224:225] op_sel_hi:[1,0]
	v_pk_fma_f32 v[146:147], v[176:177], v[94:95], v[180:181]
	v_pk_fma_f32 v[148:149], v[178:179], v[96:97], v[182:183]
	v_fmac_f32_dpp v146, v94, v172 row_shr:1 row_mask:0xf bank_mask:0xf bound_ctrl:1
	v_fmac_f32_dpp v147, v95, v173 row_shr:1 row_mask:0xf bank_mask:0xf bound_ctrl:1
	v_fmac_f32_dpp v148, v96, v174 row_shr:1 row_mask:0xf bank_mask:0xf bound_ctrl:1
	v_fmac_f32_dpp v149, v97, v175 row_shr:1 row_mask:0xf bank_mask:0xf bound_ctrl:1
	v_fmac_f32_dpp v146, v94, v168 row_shr:2 row_mask:0xf bank_mask:0xf bound_ctrl:1
	v_fmac_f32_dpp v147, v95, v169 row_shr:2 row_mask:0xf bank_mask:0xf bound_ctrl:1
	v_fmac_f32_dpp v148, v96, v170 row_shr:2 row_mask:0xf bank_mask:0xf bound_ctrl:1
	v_fmac_f32_dpp v149, v97, v171 row_shr:2 row_mask:0xf bank_mask:0xf bound_ctrl:1
	v_exp_f32_e32 v242, v146
	v_exp_f32_e32 v243, v147
	v_exp_f32_e32 v244, v148
	v_exp_f32_e32 v245, v149
	v_pk_mul_f32 v[146:147], v[146:147], v[88:89]
	v_pk_mul_f32 v[148:149], v[148:149], v[90:91]
	v_pk_add_f32 v[242:243], v[242:243], 1.0 op_sel_hi:[1,0]
	v_pk_add_f32 v[244:245], v[244:245], 1.0 op_sel_hi:[1,0]
	v_rcp_f32_e32 v242, v242
	v_rcp_f32_e32 v243, v243
	v_rcp_f32_e32 v244, v244
	v_rcp_f32_e32 v245, v245
	v_cvt_pk_bf16_f32 v90, v94, v95
	v_cvt_pk_bf16_f32 v91, v96, v97
	v_pk_mul_f32 v[146:147], v[146:147], v[242:243]
	v_pk_mul_f32 v[148:149], v[148:149], v[244:245]
	s_mov_b32 s100, 0x13400
	s_mov_b32 s101, 0
	s_and_saveexec_b64 s[6:7], s[40:41]
	v_lshl_add_u64 v[150:151], v[246:247], 0, s[100:101]
	global_store_dwordx2 v[150:151], v[90:91], off
	s_or_b64 exec, exec, s[6:7]
	v_cvt_pk_bf16_f32 v88, v146, v147
	v_cvt_pk_bf16_f32 v89, v148, v149
	v_pk_mul_f32 v[84:85], v[84:85], v[226:227] op_sel_hi:[1,0]
	v_pk_mul_f32 v[86:87], v[86:87], v[226:227] op_sel_hi:[1,0]
	v_pk_mul_f32 v[80:81], v[80:81], v[228:229] op_sel_hi:[1,0]
	v_pk_mul_f32 v[82:83], v[82:83], v[228:229] op_sel_hi:[1,0]
	v_pk_fma_f32 v[146:147], v[176:177], v[84:85], v[180:181]
	v_pk_fma_f32 v[148:149], v[178:179], v[86:87], v[182:183]
	v_fmac_f32_dpp v146, v84, v172 row_shr:1 row_mask:0xf bank_mask:0xf bound_ctrl:1
	v_fmac_f32_dpp v147, v85, v173 row_shr:1 row_mask:0xf bank_mask:0xf bound_ctrl:1
	v_fmac_f32_dpp v148, v86, v174 row_shr:1 row_mask:0xf bank_mask:0xf bound_ctrl:1
	v_fmac_f32_dpp v149, v87, v175 row_shr:1 row_mask:0xf bank_mask:0xf bound_ctrl:1
	v_fmac_f32_dpp v146, v94, v172 row_shl:15 row_mask:0xf bank_mask:0xf
	v_fmac_f32_dpp v147, v95, v173 row_shl:15 row_mask:0xf bank_mask:0xf
	v_fmac_f32_dpp v148, v96, v174 row_shl:15 row_mask:0xf bank_mask:0xf
	v_fmac_f32_dpp v149, v97, v175 row_shl:15 row_mask:0xf bank_mask:0xf
	v_fmac_f32_dpp v146, v84, v168 row_shr:2 row_mask:0xf bank_mask:0xf bound_ctrl:1
	v_fmac_f32_dpp v147, v85, v169 row_shr:2 row_mask:0xf bank_mask:0xf bound_ctrl:1
	v_fmac_f32_dpp v148, v86, v170 row_shr:2 row_mask:0xf bank_mask:0xf bound_ctrl:1
	v_fmac_f32_dpp v149, v87, v171 row_shr:2 row_mask:0xf bank_mask:0xf bound_ctrl:1
	v_fmac_f32_dpp v146, v94, v168 row_shl:14 row_mask:0xf bank_mask:0xf
	v_fmac_f32_dpp v147, v95, v169 row_shl:14 row_mask:0xf bank_mask:0xf
	v_fmac_f32_dpp v148, v96, v170 row_shl:14 row_mask:0xf bank_mask:0xf
	v_fmac_f32_dpp v149, v97, v171 row_shl:14 row_mask:0xf bank_mask:0xf
	v_exp_f32_e32 v242, v146
	v_exp_f32_e32 v243, v147
	v_exp_f32_e32 v244, v148
	v_exp_f32_e32 v245, v149
	v_pk_mul_f32 v[146:147], v[146:147], v[80:81]
	v_pk_mul_f32 v[148:149], v[148:149], v[82:83]
	v_pk_add_f32 v[242:243], v[242:243], 1.0 op_sel_hi:[1,0]
	v_pk_add_f32 v[244:245], v[244:245], 1.0 op_sel_hi:[1,0]
	v_rcp_f32_e32 v242, v242
	v_rcp_f32_e32 v243, v243
	v_rcp_f32_e32 v244, v244
	v_rcp_f32_e32 v245, v245
	s_nop 0
	v_pk_mul_f32 v[146:147], v[146:147], v[242:243]
	v_pk_mul_f32 v[148:149], v[148:149], v[244:245]
	v_cvt_pk_bf16_f32 v80, v146, v147
	v_cvt_pk_bf16_f32 v81, v148, v149
	v_pk_mul_f32 v[76:77], v[76:77], v[230:231] op_sel_hi:[1,0]
	v_pk_mul_f32 v[78:79], v[78:79], v[230:231] op_sel_hi:[1,0]
	v_pk_mul_f32 v[72:73], v[72:73], v[232:233] op_sel_hi:[1,0]
	v_pk_mul_f32 v[74:75], v[74:75], v[232:233] op_sel_hi:[1,0]
	v_pk_fma_f32 v[146:147], v[176:177], v[76:77], v[180:181]
	v_pk_fma_f32 v[148:149], v[178:179], v[78:79], v[182:183]
	v_fmac_f32_dpp v146, v76, v172 row_shr:1 row_mask:0xf bank_mask:0xf bound_ctrl:1
	v_fmac_f32_dpp v147, v77, v173 row_shr:1 row_mask:0xf bank_mask:0xf bound_ctrl:1
	v_fmac_f32_dpp v148, v78, v174 row_shr:1 row_mask:0xf bank_mask:0xf bound_ctrl:1
	v_fmac_f32_dpp v149, v79, v175 row_shr:1 row_mask:0xf bank_mask:0xf bound_ctrl:1
	v_fmac_f32_dpp v146, v84, v172 row_shl:15 row_mask:0xf bank_mask:0xf
	v_fmac_f32_dpp v147, v85, v173 row_shl:15 row_mask:0xf bank_mask:0xf
	v_fmac_f32_dpp v148, v86, v174 row_shl:15 row_mask:0xf bank_mask:0xf
	v_fmac_f32_dpp v149, v87, v175 row_shl:15 row_mask:0xf bank_mask:0xf
	v_fmac_f32_dpp v146, v76, v168 row_shr:2 row_mask:0xf bank_mask:0xf bound_ctrl:1
	v_fmac_f32_dpp v147, v77, v169 row_shr:2 row_mask:0xf bank_mask:0xf bound_ctrl:1
	v_fmac_f32_dpp v148, v78, v170 row_shr:2 row_mask:0xf bank_mask:0xf bound_ctrl:1
	v_fmac_f32_dpp v149, v79, v171 row_shr:2 row_mask:0xf bank_mask:0xf bound_ctrl:1
	v_fmac_f32_dpp v146, v84, v168 row_shl:14 row_mask:0xf bank_mask:0xf
	v_fmac_f32_dpp v147, v85, v169 row_shl:14 row_mask:0xf bank_mask:0xf
	v_fmac_f32_dpp v148, v86, v170 row_shl:14 row_mask:0xf bank_mask:0xf
	v_fmac_f32_dpp v149, v87, v171 row_shl:14 row_mask:0xf bank_mask:0xf
	v_exp_f32_e32 v242, v146
	v_exp_f32_e32 v243, v147
	v_exp_f32_e32 v244, v148
	v_exp_f32_e32 v245, v149
	v_pk_mul_f32 v[146:147], v[146:147], v[72:73]
	v_pk_mul_f32 v[148:149], v[148:149], v[74:75]
	v_pk_add_f32 v[242:243], v[242:243], 1.0 op_sel_hi:[1,0]
	v_pk_add_f32 v[244:245], v[244:245], 1.0 op_sel_hi:[1,0]
	v_rcp_f32_e32 v242, v242
	v_rcp_f32_e32 v243, v243
	v_rcp_f32_e32 v244, v244
	v_rcp_f32_e32 v245, v245
	s_nop 0
	v_pk_mul_f32 v[146:147], v[146:147], v[242:243]
	v_pk_mul_f32 v[148:149], v[148:149], v[244:245]
	v_cvt_pk_bf16_f32 v72, v146, v147
	v_cvt_pk_bf16_f32 v73, v148, v149
	v_pk_mul_f32 v[68:69], v[68:69], v[234:235] op_sel_hi:[1,0]
	v_pk_mul_f32 v[70:71], v[70:71], v[234:235] op_sel_hi:[1,0]
	v_pk_mul_f32 v[64:65], v[64:65], v[236:237] op_sel_hi:[1,0]
	v_pk_mul_f32 v[66:67], v[66:67], v[236:237] op_sel_hi:[1,0]
	v_pk_fma_f32 v[146:147], v[176:177], v[68:69], v[180:181]
	v_pk_fma_f32 v[148:149], v[178:179], v[70:71], v[182:183]
	v_fmac_f32_dpp v146, v68, v172 row_shr:1 row_mask:0xf bank_mask:0xf bound_ctrl:1
	v_fmac_f32_dpp v147, v69, v173 row_shr:1 row_mask:0xf bank_mask:0xf bound_ctrl:1
	v_fmac_f32_dpp v148, v70, v174 row_shr:1 row_mask:0xf bank_mask:0xf bound_ctrl:1
	v_fmac_f32_dpp v149, v71, v175 row_shr:1 row_mask:0xf bank_mask:0xf bound_ctrl:1
	v_fmac_f32_dpp v146, v76, v172 row_shl:15 row_mask:0xf bank_mask:0xf
	v_fmac_f32_dpp v147, v77, v173 row_shl:15 row_mask:0xf bank_mask:0xf
	v_fmac_f32_dpp v148, v78, v174 row_shl:15 row_mask:0xf bank_mask:0xf
	v_fmac_f32_dpp v149, v79, v175 row_shl:15 row_mask:0xf bank_mask:0xf
	v_fmac_f32_dpp v146, v68, v168 row_shr:2 row_mask:0xf bank_mask:0xf bound_ctrl:1
	v_fmac_f32_dpp v147, v69, v169 row_shr:2 row_mask:0xf bank_mask:0xf bound_ctrl:1
	v_fmac_f32_dpp v148, v70, v170 row_shr:2 row_mask:0xf bank_mask:0xf bound_ctrl:1
	v_fmac_f32_dpp v149, v71, v171 row_shr:2 row_mask:0xf bank_mask:0xf bound_ctrl:1
	v_fmac_f32_dpp v146, v76, v168 row_shl:14 row_mask:0xf bank_mask:0xf
	v_fmac_f32_dpp v147, v77, v169 row_shl:14 row_mask:0xf bank_mask:0xf
	v_fmac_f32_dpp v148, v78, v170 row_shl:14 row_mask:0xf bank_mask:0xf
	v_fmac_f32_dpp v149, v79, v171 row_shl:14 row_mask:0xf bank_mask:0xf
	v_exp_f32_e32 v242, v146
	v_exp_f32_e32 v243, v147
	v_exp_f32_e32 v244, v148
	v_exp_f32_e32 v245, v149
	v_pk_mul_f32 v[146:147], v[146:147], v[64:65]
	v_pk_mul_f32 v[148:149], v[148:149], v[66:67]
	v_pk_add_f32 v[242:243], v[242:243], 1.0 op_sel_hi:[1,0]
	v_pk_add_f32 v[244:245], v[244:245], 1.0 op_sel_hi:[1,0]
	v_rcp_f32_e32 v242, v242
	v_rcp_f32_e32 v243, v243
	v_rcp_f32_e32 v244, v244
	v_rcp_f32_e32 v245, v245
	v_cvt_pk_bf16_f32 v66, v68, v69
	v_cvt_pk_bf16_f32 v67, v70, v71
	v_pk_mul_f32 v[146:147], v[146:147], v[242:243]
	v_pk_mul_f32 v[148:149], v[148:149], v[244:245]
	s_mov_b32 s100, 0xffffd400
	s_mov_b32 s101, -1
	s_and_saveexec_b64 s[6:7], s[42:43]
	v_lshl_add_u64 v[150:151], v[246:247], 0, s[100:101]
	global_store_dwordx2 v[150:151], v[66:67], off
	s_or_b64 exec, exec, s[6:7]
	v_cvt_pk_bf16_f32 v64, v146, v147
	v_cvt_pk_bf16_f32 v65, v148, v149
	s_and_saveexec_b64 s[6:7], s[40:41]
	v_pk_mul_f32 v[242:243], v[56:57], v[206:207] op_sel_hi:[1,0]
	v_pk_mul_f32 v[244:245], v[58:59], v[206:207] op_sel_hi:[1,0]
	s_mov_b32 s100, 0x5808
	s_mov_b32 s101, 0
	v_cvt_pk_bf16_f32 v242, v242, v243
	v_cvt_pk_bf16_f32 v243, v244, v245
	v_lshl_add_u64 v[150:151], v[246:247], 0, s[100:101]
	global_store_dwordx2 v[150:151], v[242:243], off
	s_or_b64 exec, exec, s[6:7]
	v_pk_mul_f32 v[60:61], v[60:61], v[206:207] op_sel_hi:[1,0]
	v_pk_mul_f32 v[62:63], v[62:63], v[206:207] op_sel_hi:[1,0]
	v_pk_mul_f32 v[56:57], v[56:57], v[208:209] op_sel_hi:[1,0]
	v_pk_mul_f32 v[58:59], v[58:59], v[208:209] op_sel_hi:[1,0]
	v_pk_fma_f32 v[146:147], v[200:201], v[60:61], v[238:239]
	v_pk_fma_f32 v[148:149], v[202:203], v[62:63], v[240:241]
	v_fmac_f32_dpp v146, v60, v196 row_shr:1 row_mask:0xf bank_mask:0xf bound_ctrl:1
	v_fmac_f32_dpp v147, v61, v197 row_shr:1 row_mask:0xf bank_mask:0xf bound_ctrl:1
	v_fmac_f32_dpp v148, v62, v198 row_shr:1 row_mask:0xf bank_mask:0xf bound_ctrl:1
	v_fmac_f32_dpp v149, v63, v199 row_shr:1 row_mask:0xf bank_mask:0xf bound_ctrl:1
	v_fmac_f32_dpp v146, v60, v192 row_shr:2 row_mask:0xf bank_mask:0xf bound_ctrl:1
	v_fmac_f32_dpp v147, v61, v193 row_shr:2 row_mask:0xf bank_mask:0xf bound_ctrl:1
	v_fmac_f32_dpp v148, v62, v194 row_shr:2 row_mask:0xf bank_mask:0xf bound_ctrl:1
	v_fmac_f32_dpp v149, v63, v195 row_shr:2 row_mask:0xf bank_mask:0xf bound_ctrl:1
	v_exp_f32_e32 v242, v146
	v_exp_f32_e32 v243, v147
	v_exp_f32_e32 v244, v148
	v_exp_f32_e32 v245, v149
	v_pk_mul_f32 v[146:147], v[146:147], v[56:57]
	v_pk_mul_f32 v[148:149], v[148:149], v[58:59]
	v_pk_add_f32 v[242:243], v[242:243], 1.0 op_sel_hi:[1,0]
	v_pk_add_f32 v[244:245], v[244:245], 1.0 op_sel_hi:[1,0]
	v_rcp_f32_e32 v242, v242
	v_rcp_f32_e32 v243, v243
	v_rcp_f32_e32 v244, v244
	v_rcp_f32_e32 v245, v245
	v_cvt_pk_bf16_f32 v56, v60, v61
	v_cvt_pk_bf16_f32 v57, v62, v63
	v_pk_mul_f32 v[146:147], v[146:147], v[242:243]
	v_pk_mul_f32 v[148:149], v[148:149], v[244:245]
	s_mov_b32 s100, 0x2c08
	s_mov_b32 s101, 0
	s_and_saveexec_b64 s[6:7], s[40:41]
	v_lshl_add_u64 v[150:151], v[246:247], 0, s[100:101]
	global_store_dwordx2 v[150:151], v[56:57], off
	s_or_b64 exec, exec, s[6:7]
	v_cvt_pk_bf16_f32 v126, v146, v147
	v_cvt_pk_bf16_f32 v127, v148, v149
	s_mov_b32 s5, 0x0
	s_and_saveexec_b64 s[6:7], s[38:39]
	buffer_store_dwordx4 v[124:127], v185, s[52:55], s5 offen sc1
	s_or_b64 exec, exec, s[6:7]
	v_pk_mul_f32 v[52:53], v[52:53], v[210:211] op_sel_hi:[1,0]
	v_pk_mul_f32 v[54:55], v[54:55], v[210:211] op_sel_hi:[1,0]
	v_pk_mul_f32 v[48:49], v[48:49], v[212:213] op_sel_hi:[1,0]
	v_pk_mul_f32 v[50:51], v[50:51], v[212:213] op_sel_hi:[1,0]
	v_pk_fma_f32 v[146:147], v[200:201], v[52:53], v[238:239]
	v_pk_fma_f32 v[148:149], v[202:203], v[54:55], v[240:241]
	v_fmac_f32_dpp v146, v52, v196 row_shr:1 row_mask:0xf bank_mask:0xf bound_ctrl:1
	v_fmac_f32_dpp v147, v53, v197 row_shr:1 row_mask:0xf bank_mask:0xf bound_ctrl:1
	v_fmac_f32_dpp v148, v54, v198 row_shr:1 row_mask:0xf bank_mask:0xf bound_ctrl:1
	v_fmac_f32_dpp v149, v55, v199 row_shr:1 row_mask:0xf bank_mask:0xf bound_ctrl:1
	v_fmac_f32_dpp v146, v60, v196 row_shl:15 row_mask:0xf bank_mask:0xf
	v_fmac_f32_dpp v147, v61, v197 row_shl:15 row_mask:0xf bank_mask:0xf
	v_fmac_f32_dpp v148, v62, v198 row_shl:15 row_mask:0xf bank_mask:0xf
	v_fmac_f32_dpp v149, v63, v199 row_shl:15 row_mask:0xf bank_mask:0xf
	v_fmac_f32_dpp v146, v52, v192 row_shr:2 row_mask:0xf bank_mask:0xf bound_ctrl:1
	v_fmac_f32_dpp v147, v53, v193 row_shr:2 row_mask:0xf bank_mask:0xf bound_ctrl:1
	v_fmac_f32_dpp v148, v54, v194 row_shr:2 row_mask:0xf bank_mask:0xf bound_ctrl:1
	v_fmac_f32_dpp v149, v55, v195 row_shr:2 row_mask:0xf bank_mask:0xf bound_ctrl:1
	v_fmac_f32_dpp v146, v60, v192 row_shl:14 row_mask:0xf bank_mask:0xf
	v_fmac_f32_dpp v147, v61, v193 row_shl:14 row_mask:0xf bank_mask:0xf
	v_fmac_f32_dpp v148, v62, v194 row_shl:14 row_mask:0xf bank_mask:0xf
	v_fmac_f32_dpp v149, v63, v195 row_shl:14 row_mask:0xf bank_mask:0xf
	v_exp_f32_e32 v242, v146
	v_exp_f32_e32 v243, v147
	v_exp_f32_e32 v244, v148
	v_exp_f32_e32 v245, v149
	v_pk_mul_f32 v[146:147], v[146:147], v[48:49]
	v_pk_mul_f32 v[148:149], v[148:149], v[50:51]
	v_pk_add_f32 v[242:243], v[242:243], 1.0 op_sel_hi:[1,0]
	v_pk_add_f32 v[244:245], v[244:245], 1.0 op_sel_hi:[1,0]
	v_rcp_f32_e32 v242, v242
	v_rcp_f32_e32 v243, v243
	v_rcp_f32_e32 v244, v244
	v_rcp_f32_e32 v245, v245
	s_nop 0
	v_pk_mul_f32 v[146:147], v[146:147], v[242:243]
	v_pk_mul_f32 v[148:149], v[148:149], v[244:245]
	v_cvt_pk_bf16_f32 v118, v146, v147
	v_cvt_pk_bf16_f32 v119, v148, v149
	s_mov_b32 s5, 0x16000
	buffer_store_dwordx4 v[116:119], v185, s[52:55], s5 offen sc1
	v_pk_mul_f32 v[44:45], v[44:45], v[214:215] op_sel_hi:[1,0]
	v_pk_mul_f32 v[46:47], v[46:47], v[214:215] op_sel_hi:[1,0]
	v_pk_mul_f32 v[40:41], v[40:41], v[216:217] op_sel_hi:[1,0]
	v_pk_mul_f32 v[42:43], v[42:43], v[216:217] op_sel_hi:[1,0]
	v_pk_fma_f32 v[146:147], v[200:201], v[44:45], v[238:239]
	v_pk_fma_f32 v[148:149], v[202:203], v[46:47], v[240:241]
	v_fmac_f32_dpp v146, v44, v196 row_shr:1 row_mask:0xf bank_mask:0xf bound_ctrl:1
	v_fmac_f32_dpp v147, v45, v197 row_shr:1 row_mask:0xf bank_mask:0xf bound_ctrl:1
	v_fmac_f32_dpp v148, v46, v198 row_shr:1 row_mask:0xf bank_mask:0xf bound_ctrl:1
	v_fmac_f32_dpp v149, v47, v199 row_shr:1 row_mask:0xf bank_mask:0xf bound_ctrl:1
	v_fmac_f32_dpp v146, v52, v196 row_shl:15 row_mask:0xf bank_mask:0xf
	v_fmac_f32_dpp v147, v53, v197 row_shl:15 row_mask:0xf bank_mask:0xf
	v_fmac_f32_dpp v148, v54, v198 row_shl:15 row_mask:0xf bank_mask:0xf
	v_fmac_f32_dpp v149, v55, v199 row_shl:15 row_mask:0xf bank_mask:0xf
	v_fmac_f32_dpp v146, v44, v192 row_shr:2 row_mask:0xf bank_mask:0xf bound_ctrl:1
	v_fmac_f32_dpp v147, v45, v193 row_shr:2 row_mask:0xf bank_mask:0xf bound_ctrl:1
	v_fmac_f32_dpp v148, v46, v194 row_shr:2 row_mask:0xf bank_mask:0xf bound_ctrl:1
	v_fmac_f32_dpp v149, v47, v195 row_shr:2 row_mask:0xf bank_mask:0xf bound_ctrl:1
	v_fmac_f32_dpp v146, v52, v192 row_shl:14 row_mask:0xf bank_mask:0xf
	v_fmac_f32_dpp v147, v53, v193 row_shl:14 row_mask:0xf bank_mask:0xf
	v_fmac_f32_dpp v148, v54, v194 row_shl:14 row_mask:0xf bank_mask:0xf
	v_fmac_f32_dpp v149, v55, v195 row_shl:14 row_mask:0xf bank_mask:0xf
	v_exp_f32_e32 v242, v146
	v_exp_f32_e32 v243, v147
	v_exp_f32_e32 v244, v148
	v_exp_f32_e32 v245, v149
	v_pk_mul_f32 v[146:147], v[146:147], v[40:41]
	v_pk_mul_f32 v[148:149], v[148:149], v[42:43]
	v_pk_add_f32 v[242:243], v[242:243], 1.0 op_sel_hi:[1,0]
	v_pk_add_f32 v[244:245], v[244:245], 1.0 op_sel_hi:[1,0]
	v_rcp_f32_e32 v242, v242
	v_rcp_f32_e32 v243, v243
	v_rcp_f32_e32 v244, v244
	v_rcp_f32_e32 v245, v245
	s_nop 0
	v_pk_mul_f32 v[146:147], v[146:147], v[242:243]
	v_pk_mul_f32 v[148:149], v[148:149], v[244:245]
	v_cvt_pk_bf16_f32 v100, v146, v147
	v_cvt_pk_bf16_f32 v101, v148, v149
	s_mov_b32 s5, 0x2c000
	buffer_store_dwordx4 v[98:101], v185, s[52:55], s5 offen sc1
	v_pk_mul_f32 v[36:37], v[36:37], v[218:219] op_sel_hi:[1,0]
	v_pk_mul_f32 v[38:39], v[38:39], v[218:219] op_sel_hi:[1,0]
	v_pk_mul_f32 v[32:33], v[32:33], v[220:221] op_sel_hi:[1,0]
	v_pk_mul_f32 v[34:35], v[34:35], v[220:221] op_sel_hi:[1,0]
	v_pk_fma_f32 v[146:147], v[200:201], v[36:37], v[238:239]
	v_pk_fma_f32 v[148:149], v[202:203], v[38:39], v[240:241]
	v_fmac_f32_dpp v146, v36, v196 row_shr:1 row_mask:0xf bank_mask:0xf bound_ctrl:1
	v_fmac_f32_dpp v147, v37, v197 row_shr:1 row_mask:0xf bank_mask:0xf bound_ctrl:1
	v_fmac_f32_dpp v148, v38, v198 row_shr:1 row_mask:0xf bank_mask:0xf bound_ctrl:1
	v_fmac_f32_dpp v149, v39, v199 row_shr:1 row_mask:0xf bank_mask:0xf bound_ctrl:1
	v_fmac_f32_dpp v146, v44, v196 row_shl:15 row_mask:0xf bank_mask:0xf
	v_fmac_f32_dpp v147, v45, v197 row_shl:15 row_mask:0xf bank_mask:0xf
	v_fmac_f32_dpp v148, v46, v198 row_shl:15 row_mask:0xf bank_mask:0xf
	v_fmac_f32_dpp v149, v47, v199 row_shl:15 row_mask:0xf bank_mask:0xf
	v_fmac_f32_dpp v146, v36, v192 row_shr:2 row_mask:0xf bank_mask:0xf bound_ctrl:1
	v_fmac_f32_dpp v147, v37, v193 row_shr:2 row_mask:0xf bank_mask:0xf bound_ctrl:1
	v_fmac_f32_dpp v148, v38, v194 row_shr:2 row_mask:0xf bank_mask:0xf bound_ctrl:1
	v_fmac_f32_dpp v149, v39, v195 row_shr:2 row_mask:0xf bank_mask:0xf bound_ctrl:1
	v_fmac_f32_dpp v146, v44, v192 row_shl:14 row_mask:0xf bank_mask:0xf
	v_fmac_f32_dpp v147, v45, v193 row_shl:14 row_mask:0xf bank_mask:0xf
	v_fmac_f32_dpp v148, v46, v194 row_shl:14 row_mask:0xf bank_mask:0xf
	v_fmac_f32_dpp v149, v47, v195 row_shl:14 row_mask:0xf bank_mask:0xf
	v_exp_f32_e32 v242, v146
	v_exp_f32_e32 v243, v147
	v_exp_f32_e32 v244, v148
	v_exp_f32_e32 v245, v149
	v_pk_mul_f32 v[146:147], v[146:147], v[32:33]
	v_pk_mul_f32 v[148:149], v[148:149], v[34:35]
	v_pk_add_f32 v[242:243], v[242:243], 1.0 op_sel_hi:[1,0]
	v_pk_add_f32 v[244:245], v[244:245], 1.0 op_sel_hi:[1,0]
	v_rcp_f32_e32 v242, v242
	v_rcp_f32_e32 v243, v243
	v_rcp_f32_e32 v244, v244
	v_rcp_f32_e32 v245, v245
	v_cvt_pk_bf16_f32 v32, v36, v37
	v_cvt_pk_bf16_f32 v33, v38, v39
	v_pk_mul_f32 v[146:147], v[146:147], v[242:243]
	v_pk_mul_f32 v[148:149], v[148:149], v[244:245]
	s_mov_b32 s100, 0xfffecc08
	s_mov_b32 s101, -1
	s_and_saveexec_b64 s[6:7], s[42:43]
	v_lshl_add_u64 v[150:151], v[246:247], 0, s[100:101]
	global_store_dwordx2 v[150:151], v[32:33], off
	s_or_b64 exec, exec, s[6:7]
	v_cvt_pk_bf16_f32 v106, v146, v147
	v_cvt_pk_bf16_f32 v107, v148, v149
	s_mov_b32 s5, 0x42000
	buffer_store_dwordx4 v[104:107], v185, s[52:55], s5 offen sc1
	s_and_saveexec_b64 s[6:7], s[40:41]
	v_pk_mul_f32 v[242:243], v[24:25], v[222:223] op_sel_hi:[1,0]
	v_pk_mul_f32 v[244:245], v[26:27], v[222:223] op_sel_hi:[1,0]
	s_mov_b32 s100, 0x16008
	s_mov_b32 s101, 0
	v_cvt_pk_bf16_f32 v242, v242, v243
	v_cvt_pk_bf16_f32 v243, v244, v245
	v_lshl_add_u64 v[150:151], v[246:247], 0, s[100:101]
	global_store_dwordx2 v[150:151], v[242:243], off
	s_or_b64 exec, exec, s[6:7]
	v_pk_mul_f32 v[28:29], v[28:29], v[222:223] op_sel_hi:[1,0]
	v_pk_mul_f32 v[30:31], v[30:31], v[222:223] op_sel_hi:[1,0]
	v_pk_mul_f32 v[24:25], v[24:25], v[224:225] op_sel_hi:[1,0]
	v_pk_mul_f32 v[26:27], v[26:27], v[224:225] op_sel_hi:[1,0]
	v_pk_fma_f32 v[146:147], v[200:201], v[28:29], v[238:239]
	v_pk_fma_f32 v[148:149], v[202:203], v[30:31], v[240:241]
	v_fmac_f32_dpp v146, v28, v196 row_shr:1 row_mask:0xf bank_mask:0xf bound_ctrl:1
	v_fmac_f32_dpp v147, v29, v197 row_shr:1 row_mask:0xf bank_mask:0xf bound_ctrl:1
	v_fmac_f32_dpp v148, v30, v198 row_shr:1 row_mask:0xf bank_mask:0xf bound_ctrl:1
	v_fmac_f32_dpp v149, v31, v199 row_shr:1 row_mask:0xf bank_mask:0xf bound_ctrl:1
	v_fmac_f32_dpp v146, v28, v192 row_shr:2 row_mask:0xf bank_mask:0xf bound_ctrl:1
	v_fmac_f32_dpp v147, v29, v193 row_shr:2 row_mask:0xf bank_mask:0xf bound_ctrl:1
	v_fmac_f32_dpp v148, v30, v194 row_shr:2 row_mask:0xf bank_mask:0xf bound_ctrl:1
	v_fmac_f32_dpp v149, v31, v195 row_shr:2 row_mask:0xf bank_mask:0xf bound_ctrl:1
	v_exp_f32_e32 v242, v146
	v_exp_f32_e32 v243, v147
	v_exp_f32_e32 v244, v148
	v_exp_f32_e32 v245, v149
	v_pk_mul_f32 v[146:147], v[146:147], v[24:25]
	v_pk_mul_f32 v[148:149], v[148:149], v[26:27]
	v_pk_add_f32 v[242:243], v[242:243], 1.0 op_sel_hi:[1,0]
	v_pk_add_f32 v[244:245], v[244:245], 1.0 op_sel_hi:[1,0]
	v_rcp_f32_e32 v242, v242
	v_rcp_f32_e32 v243, v243
	v_rcp_f32_e32 v244, v244
	v_rcp_f32_e32 v245, v245
	v_cvt_pk_bf16_f32 v24, v28, v29
	v_cvt_pk_bf16_f32 v25, v30, v31
	v_pk_mul_f32 v[146:147], v[146:147], v[242:243]
	v_pk_mul_f32 v[148:149], v[148:149], v[244:245]
	s_mov_b32 s100, 0x13408
	s_mov_b32 s101, 0
	s_and_saveexec_b64 s[6:7], s[40:41]
	v_lshl_add_u64 v[150:151], v[246:247], 0, s[100:101]
	global_store_dwordx2 v[150:151], v[24:25], off
	s_or_b64 exec, exec, s[6:7]
	v_cvt_pk_bf16_f32 v90, v146, v147
	v_cvt_pk_bf16_f32 v91, v148, v149
	s_mov_b32 s5, 0xb0000
	s_and_saveexec_b64 s[6:7], s[38:39]
	buffer_store_dwordx4 v[88:91], v185, s[52:55], s5 offen sc1
	s_or_b64 exec, exec, s[6:7]
	v_pk_mul_f32 v[20:21], v[20:21], v[226:227] op_sel_hi:[1,0]
	v_pk_mul_f32 v[22:23], v[22:23], v[226:227] op_sel_hi:[1,0]
	v_pk_mul_f32 v[16:17], v[16:17], v[228:229] op_sel_hi:[1,0]
	v_pk_mul_f32 v[18:19], v[18:19], v[228:229] op_sel_hi:[1,0]
	v_pk_fma_f32 v[146:147], v[200:201], v[20:21], v[238:239]
	v_pk_fma_f32 v[148:149], v[202:203], v[22:23], v[240:241]
	v_fmac_f32_dpp v146, v20, v196 row_shr:1 row_mask:0xf bank_mask:0xf bound_ctrl:1
	v_fmac_f32_dpp v147, v21, v197 row_shr:1 row_mask:0xf bank_mask:0xf bound_ctrl:1
	v_fmac_f32_dpp v148, v22, v198 row_shr:1 row_mask:0xf bank_mask:0xf bound_ctrl:1
	v_fmac_f32_dpp v149, v23, v199 row_shr:1 row_mask:0xf bank_mask:0xf bound_ctrl:1
	v_fmac_f32_dpp v146, v28, v196 row_shl:15 row_mask:0xf bank_mask:0xf
	v_fmac_f32_dpp v147, v29, v197 row_shl:15 row_mask:0xf bank_mask:0xf
	v_fmac_f32_dpp v148, v30, v198 row_shl:15 row_mask:0xf bank_mask:0xf
	v_fmac_f32_dpp v149, v31, v199 row_shl:15 row_mask:0xf bank_mask:0xf
	v_fmac_f32_dpp v146, v20, v192 row_shr:2 row_mask:0xf bank_mask:0xf bound_ctrl:1
	v_fmac_f32_dpp v147, v21, v193 row_shr:2 row_mask:0xf bank_mask:0xf bound_ctrl:1
	v_fmac_f32_dpp v148, v22, v194 row_shr:2 row_mask:0xf bank_mask:0xf bound_ctrl:1
	v_fmac_f32_dpp v149, v23, v195 row_shr:2 row_mask:0xf bank_mask:0xf bound_ctrl:1
	v_fmac_f32_dpp v146, v28, v192 row_shl:14 row_mask:0xf bank_mask:0xf
	v_fmac_f32_dpp v147, v29, v193 row_shl:14 row_mask:0xf bank_mask:0xf
	v_fmac_f32_dpp v148, v30, v194 row_shl:14 row_mask:0xf bank_mask:0xf
	v_fmac_f32_dpp v149, v31, v195 row_shl:14 row_mask:0xf bank_mask:0xf
	v_exp_f32_e32 v242, v146
	v_exp_f32_e32 v243, v147
	v_exp_f32_e32 v244, v148
	v_exp_f32_e32 v245, v149
	v_pk_mul_f32 v[146:147], v[146:147], v[16:17]
	v_pk_mul_f32 v[148:149], v[148:149], v[18:19]
	v_pk_add_f32 v[242:243], v[242:243], 1.0 op_sel_hi:[1,0]
	v_pk_add_f32 v[244:245], v[244:245], 1.0 op_sel_hi:[1,0]
	v_rcp_f32_e32 v242, v242
	v_rcp_f32_e32 v243, v243
	v_rcp_f32_e32 v244, v244
	v_rcp_f32_e32 v245, v245
	s_nop 0
	v_pk_mul_f32 v[146:147], v[146:147], v[242:243]
	v_pk_mul_f32 v[148:149], v[148:149], v[244:245]
	v_cvt_pk_bf16_f32 v82, v146, v147
	v_cvt_pk_bf16_f32 v83, v148, v149
	s_mov_b32 s5, 0xc6000
	buffer_store_dwordx4 v[80:83], v185, s[52:55], s5 offen sc1
	v_pk_mul_f32 v[12:13], v[12:13], v[230:231] op_sel_hi:[1,0]
	v_pk_mul_f32 v[14:15], v[14:15], v[230:231] op_sel_hi:[1,0]
	v_pk_mul_f32 v[8:9], v[8:9], v[232:233] op_sel_hi:[1,0]
	v_pk_mul_f32 v[10:11], v[10:11], v[232:233] op_sel_hi:[1,0]
	v_pk_fma_f32 v[146:147], v[200:201], v[12:13], v[238:239]
	v_pk_fma_f32 v[148:149], v[202:203], v[14:15], v[240:241]
	v_fmac_f32_dpp v146, v12, v196 row_shr:1 row_mask:0xf bank_mask:0xf bound_ctrl:1
	v_fmac_f32_dpp v147, v13, v197 row_shr:1 row_mask:0xf bank_mask:0xf bound_ctrl:1
	v_fmac_f32_dpp v148, v14, v198 row_shr:1 row_mask:0xf bank_mask:0xf bound_ctrl:1
	v_fmac_f32_dpp v149, v15, v199 row_shr:1 row_mask:0xf bank_mask:0xf bound_ctrl:1
	v_fmac_f32_dpp v146, v20, v196 row_shl:15 row_mask:0xf bank_mask:0xf
	v_fmac_f32_dpp v147, v21, v197 row_shl:15 row_mask:0xf bank_mask:0xf
	v_fmac_f32_dpp v148, v22, v198 row_shl:15 row_mask:0xf bank_mask:0xf
	v_fmac_f32_dpp v149, v23, v199 row_shl:15 row_mask:0xf bank_mask:0xf
	v_fmac_f32_dpp v146, v12, v192 row_shr:2 row_mask:0xf bank_mask:0xf bound_ctrl:1
	v_fmac_f32_dpp v147, v13, v193 row_shr:2 row_mask:0xf bank_mask:0xf bound_ctrl:1
	v_fmac_f32_dpp v148, v14, v194 row_shr:2 row_mask:0xf bank_mask:0xf bound_ctrl:1
	v_fmac_f32_dpp v149, v15, v195 row_shr:2 row_mask:0xf bank_mask:0xf bound_ctrl:1
	v_fmac_f32_dpp v146, v20, v192 row_shl:14 row_mask:0xf bank_mask:0xf
	v_fmac_f32_dpp v147, v21, v193 row_shl:14 row_mask:0xf bank_mask:0xf
	v_fmac_f32_dpp v148, v22, v194 row_shl:14 row_mask:0xf bank_mask:0xf
	v_fmac_f32_dpp v149, v23, v195 row_shl:14 row_mask:0xf bank_mask:0xf
	v_exp_f32_e32 v242, v146
	v_exp_f32_e32 v243, v147
	v_exp_f32_e32 v244, v148
	v_exp_f32_e32 v245, v149
	v_pk_mul_f32 v[146:147], v[146:147], v[8:9]
	v_pk_mul_f32 v[148:149], v[148:149], v[10:11]
	v_pk_add_f32 v[242:243], v[242:243], 1.0 op_sel_hi:[1,0]
	v_pk_add_f32 v[244:245], v[244:245], 1.0 op_sel_hi:[1,0]
	v_rcp_f32_e32 v242, v242
	v_rcp_f32_e32 v243, v243
	v_rcp_f32_e32 v244, v244
	v_rcp_f32_e32 v245, v245
	s_nop 0
	v_pk_mul_f32 v[146:147], v[146:147], v[242:243]
	v_pk_mul_f32 v[148:149], v[148:149], v[244:245]
	v_cvt_pk_bf16_f32 v74, v146, v147
	v_cvt_pk_bf16_f32 v75, v148, v149
	s_mov_b32 s5, 0xdc000
	buffer_store_dwordx4 v[72:75], v185, s[52:55], s5 offen sc1
	v_pk_mul_f32 v[4:5], v[4:5], v[234:235] op_sel_hi:[1,0]
	v_pk_mul_f32 v[6:7], v[6:7], v[234:235] op_sel_hi:[1,0]
	v_pk_mul_f32 v[0:1], v[0:1], v[236:237] op_sel_hi:[1,0]
	v_pk_mul_f32 v[2:3], v[2:3], v[236:237] op_sel_hi:[1,0]
	v_pk_fma_f32 v[146:147], v[200:201], v[4:5], v[238:239]
	v_pk_fma_f32 v[148:149], v[202:203], v[6:7], v[240:241]
	v_fmac_f32_dpp v146, v4, v196 row_shr:1 row_mask:0xf bank_mask:0xf bound_ctrl:1
	v_fmac_f32_dpp v147, v5, v197 row_shr:1 row_mask:0xf bank_mask:0xf bound_ctrl:1
	v_fmac_f32_dpp v148, v6, v198 row_shr:1 row_mask:0xf bank_mask:0xf bound_ctrl:1
	v_fmac_f32_dpp v149, v7, v199 row_shr:1 row_mask:0xf bank_mask:0xf bound_ctrl:1
	v_fmac_f32_dpp v146, v12, v196 row_shl:15 row_mask:0xf bank_mask:0xf
	v_fmac_f32_dpp v147, v13, v197 row_shl:15 row_mask:0xf bank_mask:0xf
	v_fmac_f32_dpp v148, v14, v198 row_shl:15 row_mask:0xf bank_mask:0xf
	v_fmac_f32_dpp v149, v15, v199 row_shl:15 row_mask:0xf bank_mask:0xf
	v_fmac_f32_dpp v146, v4, v192 row_shr:2 row_mask:0xf bank_mask:0xf bound_ctrl:1
	v_fmac_f32_dpp v147, v5, v193 row_shr:2 row_mask:0xf bank_mask:0xf bound_ctrl:1
	v_fmac_f32_dpp v148, v6, v194 row_shr:2 row_mask:0xf bank_mask:0xf bound_ctrl:1
	v_fmac_f32_dpp v149, v7, v195 row_shr:2 row_mask:0xf bank_mask:0xf bound_ctrl:1
	v_fmac_f32_dpp v146, v12, v192 row_shl:14 row_mask:0xf bank_mask:0xf
	v_fmac_f32_dpp v147, v13, v193 row_shl:14 row_mask:0xf bank_mask:0xf
	v_fmac_f32_dpp v148, v14, v194 row_shl:14 row_mask:0xf bank_mask:0xf
	v_fmac_f32_dpp v149, v15, v195 row_shl:14 row_mask:0xf bank_mask:0xf
	v_exp_f32_e32 v242, v146
	v_exp_f32_e32 v243, v147
	v_exp_f32_e32 v244, v148
	v_exp_f32_e32 v245, v149
	v_pk_mul_f32 v[146:147], v[146:147], v[0:1]
	v_pk_mul_f32 v[148:149], v[148:149], v[2:3]
	v_pk_add_f32 v[242:243], v[242:243], 1.0 op_sel_hi:[1,0]
	v_pk_add_f32 v[244:245], v[244:245], 1.0 op_sel_hi:[1,0]
	v_rcp_f32_e32 v242, v242
	v_rcp_f32_e32 v243, v243
	v_rcp_f32_e32 v244, v244
	v_rcp_f32_e32 v245, v245
	v_cvt_pk_bf16_f32 v0, v4, v5
	v_cvt_pk_bf16_f32 v1, v6, v7
	v_pk_mul_f32 v[146:147], v[146:147], v[242:243]
	v_pk_mul_f32 v[148:149], v[148:149], v[244:245]
	s_mov_b32 s100, 0xffffd408
	s_mov_b32 s101, -1
	s_and_saveexec_b64 s[6:7], s[42:43]
	v_lshl_add_u64 v[150:151], v[246:247], 0, s[100:101]
	global_store_dwordx2 v[150:151], v[0:1], off
	s_or_b64 exec, exec, s[6:7]
	v_cvt_pk_bf16_f32 v66, v146, v147
	v_cvt_pk_bf16_f32 v67, v148, v149
	s_mov_b32 s5, 0xf2000
	buffer_store_dwordx4 v[64:67], v185, s[52:55], s5 offen sc1
	s_andn2_b64 vcc, exec, s[44:45]
	s_mov_b64 s[6:7], -1
	s_cbranch_vccnz .LBB0_716
	s_andn2_b64 vcc, exec, s[28:29]
	s_cbranch_vccnz .LBB0_715
	s_barrier
	s_branch .LBB0_715

.LBB0_1046:
	s_cmp_lt_i32 s30, s27
	s_cselect_b64 s[4:5], -1, 0
	s_cmp_gt_i32 s30, s3
	s_cselect_b64 s[6:7], -1, 0
	s_or_b64 s[4:5], s[4:5], s[6:7]
	s_and_b64 vcc, exec, s[4:5]
	s_cbranch_vccnz .LBB0_1056
	ds_read_b128 v[64:67], v125
	ds_read_b128 v[72:75], v125 offset:64
	s_add_i32 s4, s28, s30
	s_add_i32 s4, s4, 8
	s_cmp_lt_i32 s4, 6
	s_cselect_b64 s[4:5], -1, 0
	s_mov_b64 s[8:9], -1
	s_and_b64 vcc, exec, s[4:5]
	s_waitcnt lgkmcnt(1)
	v_mfma_f32_16x16x32_bf16 v[68:71], v[64:67], v[0:3], 0
	ds_read_b128 v[76:79], v125 offset:4672
	ds_read_b128 v[80:83], v125 offset:6976
	v_mfma_f32_16x16x32_bf16 v[64:67], v[64:67], v[8:11], 0
	s_waitcnt lgkmcnt(2)
	v_mfma_f32_16x16x32_bf16 v[84:87], v[72:75], v[12:15], v[64:67]
	v_mfma_f32_16x16x32_bf16 v[108:111], v[72:75], v[4:7], v[68:71]
	s_nop 4
	ds_read_b128 v[64:67], v125 offset:2304
	ds_read_b128 v[72:75], v125 offset:2368
	s_waitcnt lgkmcnt(1)
	v_mfma_f32_16x16x32_bf16 v[68:71], v[64:67], v[0:3], 0
	v_mfma_f32_16x16x32_bf16 v[64:67], v[64:67], v[8:11], 0
	s_waitcnt lgkmcnt(0)
	v_mfma_f32_16x16x32_bf16 v[104:107], v[72:75], v[4:7], v[68:71]
	v_mfma_f32_16x16x32_bf16 v[72:75], v[72:75], v[12:15], v[64:67]
	s_nop 4
	ds_read_b128 v[64:67], v125 offset:4608
	s_waitcnt lgkmcnt(0)
	v_mfma_f32_16x16x32_bf16 v[68:71], v[64:67], v[0:3], 0
	v_mfma_f32_16x16x32_bf16 v[64:67], v[64:67], v[8:11], 0
	v_mfma_f32_16x16x32_bf16 v[100:103], v[76:79], v[4:7], v[68:71]
	v_mfma_f32_16x16x32_bf16 v[68:71], v[76:79], v[12:15], v[64:67]
	s_nop 5
	ds_read_b128 v[64:67], v125 offset:6912
	s_waitcnt lgkmcnt(0)
	v_mfma_f32_16x16x32_bf16 v[76:79], v[64:67], v[0:3], 0
	v_mfma_f32_16x16x32_bf16 v[64:67], v[64:67], v[8:11], 0
	v_mfma_f32_16x16x32_bf16 v[96:99], v[80:83], v[4:7], v[76:79]
	v_mfma_f32_16x16x32_bf16 v[64:67], v[80:83], v[12:15], v[64:67]
	s_cbranch_vccz .LBB0_1072
	s_nop 3
	v_max3_f32 v77, v108, v109, v110
	v_max3_f32 v78, v104, v105, v106
	v_max3_f32 v77, v77, v111, v107
	v_max3_f32 v77, v77, v78, s95
	v_max3_f32 v78, v100, v101, v102
	v_max3_f32 v79, v96, v97, v98
	v_max3_f32 v78, v78, v103, v99
	v_max3_f32 v77, v77, v78, v79
	v_mov_b32_e32 v78, v77
	s_nop 1
	v_permlane16_swap_b32_e32 v77, v78
	ds_read_b32 v76, v153 offset:37628
	v_max_f32_e32 v77, v77, v78
	v_mov_b32_e32 v78, v77
	s_nop 1
	v_permlane32_swap_b32_e32 v77, v78
	v_max_f32_e32 v77, v77, v78
	s_waitcnt lgkmcnt(0)
	v_fmamk_f32 v77, v77, 0x3e38aa3b, v76
	v_sub_f32_e32 v78, v77, v139
	v_cmp_ge_f32_e32 vcc, s97, v78
	v_max_f32_e32 v78, v139, v139
	v_max_f32_e32 v77, v78, v77
	s_cmp_lg_u64 vcc, exec
	v_sub_f32_e32 v78, v139, v77
	s_cselect_b64 s[6:7], -1, 0
	v_exp_f32_e32 v78, v78
	v_cndmask_b32_e64 v145, v139, v77, s[6:7]
	s_mov_b32 s100, 0x3e38aa3b
	v_sub_f32_e32 v170, v76, v145
	v_cndmask_b32_e64 v142, 1.0, v78, s[6:7]
	v_pk_fma_f32 v[76:77], v[108:109], s[100:101], v[170:171] op_sel_hi:[1,0,0]
	v_pk_fma_f32 v[78:79], v[110:111], s[100:101], v[170:171] op_sel_hi:[1,0,0]
	v_pk_fma_f32 v[80:81], v[104:105], s[100:101], v[170:171] op_sel_hi:[1,0,0]
	v_pk_fma_f32 v[82:83], v[106:107], s[100:101], v[170:171] op_sel_hi:[1,0,0]
	v_pk_fma_f32 v[88:89], v[100:101], s[100:101], v[170:171] op_sel_hi:[1,0,0]
	v_pk_fma_f32 v[90:91], v[102:103], s[100:101], v[170:171] op_sel_hi:[1,0,0]
	v_pk_fma_f32 v[92:93], v[96:97], s[100:101], v[170:171] op_sel_hi:[1,0,0]
	v_pk_fma_f32 v[94:95], v[98:99], s[100:101], v[170:171] op_sel_hi:[1,0,0]
	v_exp_f32_e32 v76, v76
	v_exp_f32_e32 v77, v77
	v_exp_f32_e32 v78, v78
	v_exp_f32_e32 v79, v79
	v_exp_f32_e32 v80, v80
	v_exp_f32_e32 v81, v81
	v_exp_f32_e32 v82, v82
	v_exp_f32_e32 v83, v83
	v_exp_f32_e32 v88, v88
	v_exp_f32_e32 v89, v89
	v_exp_f32_e32 v90, v90
	v_exp_f32_e32 v91, v91
	v_exp_f32_e32 v92, v92
	v_exp_f32_e32 v93, v93
	v_exp_f32_e32 v94, v94
	v_exp_f32_e32 v95, v95
	v_pk_add_f32 v[172:173], v[76:77], v[78:79]
	v_pk_add_f32 v[174:175], v[80:81], v[82:83]
	v_pk_add_f32 v[172:173], v[172:173], v[88:89]
	v_pk_add_f32 v[174:175], v[174:175], v[90:91]
	v_pk_add_f32 v[172:173], v[172:173], v[92:93]
	v_pk_add_f32 v[174:175], v[174:175], v[94:95]
	v_pk_add_f32 v[172:173], v[172:173], v[174:175]
	v_add_f32_e32 v147, v172, v173
	s_cbranch_execz .LBB0_1073

.LBB0_1051:
	s_andn2_b64 vcc, exec, s[4:5]
	s_mov_b64 s[6:7], -1
	s_cbranch_vccnz .LBB0_1074
	v_max3_f32 v97, v84, v85, v86
	v_max3_f32 v98, v72, v73, v74
	v_max3_f32 v97, v97, v87, v75
	v_max3_f32 v97, v97, v98, s95
	v_max3_f32 v98, v68, v69, v70
	v_max3_f32 v99, v64, v65, v66
	v_max3_f32 v98, v98, v71, v67
	v_max3_f32 v97, v97, v98, v99
	v_mov_b32_e32 v98, v97
	s_nop 1
	v_permlane16_swap_b32_e32 v97, v98
	ds_read_b32 v96, v153 offset:37628
	v_max_f32_e32 v97, v97, v98
	v_mov_b32_e32 v98, v97
	s_nop 1
	v_permlane32_swap_b32_e32 v97, v98
	v_max_f32_e32 v97, v97, v98
	s_waitcnt lgkmcnt(0)
	v_fmamk_f32 v97, v97, 0x3e38aa3b, v96
	v_sub_f32_e32 v98, v97, v137
	v_cmp_ge_f32_e32 vcc, s97, v98
	v_max_f32_e32 v98, v137, v137
	v_max_f32_e32 v97, v98, v97
	s_cmp_lg_u64 vcc, exec
	v_sub_f32_e32 v98, v137, v97
	s_cselect_b64 s[4:5], -1, 0
	v_exp_f32_e32 v98, v98
	v_cndmask_b32_e64 v146, v137, v97, s[4:5]
	s_mov_b32 s100, 0x3e38aa3b
	v_sub_f32_e32 v170, v96, v146
	v_cndmask_b32_e64 v142, 1.0, v98, s[4:5]
	v_pk_fma_f32 v[96:97], v[84:85], s[100:101], v[170:171] op_sel_hi:[1,0,0]
	v_pk_fma_f32 v[98:99], v[86:87], s[100:101], v[170:171] op_sel_hi:[1,0,0]
	v_pk_fma_f32 v[100:101], v[72:73], s[100:101], v[170:171] op_sel_hi:[1,0,0]
	v_pk_fma_f32 v[102:103], v[74:75], s[100:101], v[170:171] op_sel_hi:[1,0,0]
	v_pk_fma_f32 v[104:105], v[68:69], s[100:101], v[170:171] op_sel_hi:[1,0,0]
	v_pk_fma_f32 v[106:107], v[70:71], s[100:101], v[170:171] op_sel_hi:[1,0,0]
	v_pk_fma_f32 v[108:109], v[64:65], s[100:101], v[170:171] op_sel_hi:[1,0,0]
	v_pk_fma_f32 v[110:111], v[66:67], s[100:101], v[170:171] op_sel_hi:[1,0,0]
	v_exp_f32_e32 v96, v96
	v_exp_f32_e32 v97, v97
	v_exp_f32_e32 v98, v98
	v_exp_f32_e32 v99, v99
	v_exp_f32_e32 v100, v100
	v_exp_f32_e32 v101, v101
	v_exp_f32_e32 v102, v102
	v_exp_f32_e32 v103, v103
	v_exp_f32_e32 v104, v104
	v_exp_f32_e32 v105, v105
	v_exp_f32_e32 v106, v106
	v_exp_f32_e32 v107, v107
	v_exp_f32_e32 v108, v108
	v_exp_f32_e32 v109, v109
	v_exp_f32_e32 v110, v110
	v_exp_f32_e32 v111, v111
	v_pk_add_f32 v[172:173], v[96:97], v[98:99]
	v_pk_add_f32 v[174:175], v[100:101], v[102:103]
	v_pk_add_f32 v[172:173], v[172:173], v[104:105]
	v_pk_add_f32 v[174:175], v[174:175], v[106:107]
	v_pk_add_f32 v[172:173], v[172:173], v[108:109]
	v_pk_add_f32 v[174:175], v[174:175], v[110:111]
	v_pk_add_f32 v[172:173], v[172:173], v[174:175]
	v_add_f32_e32 v139, v172, v173
	s_cbranch_execz .LBB0_1075

.LBB0_1059:
	s_cmp_lt_i32 s4, s27
	s_cselect_b64 s[4:5], -1, 0
	s_cmp_ge_i32 s30, s3
	s_cselect_b64 s[6:7], -1, 0
	s_or_b64 s[4:5], s[6:7], s[4:5]
	s_and_b64 vcc, exec, s[4:5]
	s_cbranch_vccnz .LBB0_1069
	ds_read_b128 v[64:67], v125 offset:9216
	ds_read_b128 v[72:75], v125 offset:9280
	s_add_i32 s4, s28, s30
	s_add_i32 s4, s4, 9
	s_cmp_lt_i32 s4, 6
	s_cselect_b64 s[4:5], -1, 0
	s_mov_b64 s[8:9], -1
	s_and_b64 vcc, exec, s[4:5]
	s_waitcnt lgkmcnt(1)
	v_mfma_f32_16x16x32_bf16 v[68:71], v[64:67], v[0:3], 0
	ds_read_b128 v[76:79], v125 offset:13888
	ds_read_b128 v[80:83], v125 offset:16192
	v_mfma_f32_16x16x32_bf16 v[64:67], v[64:67], v[8:11], 0
	s_waitcnt lgkmcnt(2)
	v_mfma_f32_16x16x32_bf16 v[84:87], v[72:75], v[12:15], v[64:67]
	v_mfma_f32_16x16x32_bf16 v[108:111], v[72:75], v[4:7], v[68:71]
	s_nop 4
	ds_read_b128 v[64:67], v125 offset:11520
	ds_read_b128 v[72:75], v125 offset:11584
	s_waitcnt lgkmcnt(1)
	v_mfma_f32_16x16x32_bf16 v[68:71], v[64:67], v[0:3], 0
	v_mfma_f32_16x16x32_bf16 v[64:67], v[64:67], v[8:11], 0
	s_waitcnt lgkmcnt(0)
	v_mfma_f32_16x16x32_bf16 v[104:107], v[72:75], v[4:7], v[68:71]
	v_mfma_f32_16x16x32_bf16 v[72:75], v[72:75], v[12:15], v[64:67]
	s_nop 4
	ds_read_b128 v[64:67], v125 offset:13824
	s_waitcnt lgkmcnt(0)
	v_mfma_f32_16x16x32_bf16 v[68:71], v[64:67], v[0:3], 0
	v_mfma_f32_16x16x32_bf16 v[64:67], v[64:67], v[8:11], 0
	v_mfma_f32_16x16x32_bf16 v[100:103], v[76:79], v[4:7], v[68:71]
	v_mfma_f32_16x16x32_bf16 v[68:71], v[76:79], v[12:15], v[64:67]
	s_nop 5
	ds_read_b128 v[64:67], v125 offset:16128
	s_waitcnt lgkmcnt(0)
	v_mfma_f32_16x16x32_bf16 v[76:79], v[64:67], v[0:3], 0
	v_mfma_f32_16x16x32_bf16 v[64:67], v[64:67], v[8:11], 0
	v_mfma_f32_16x16x32_bf16 v[96:99], v[80:83], v[4:7], v[76:79]
	v_mfma_f32_16x16x32_bf16 v[64:67], v[80:83], v[12:15], v[64:67]
	s_cbranch_vccz .LBB0_1076
	s_nop 3
	v_max3_f32 v77, v108, v109, v110
	v_max3_f32 v78, v104, v105, v106
	v_max3_f32 v77, v77, v111, v107
	v_max3_f32 v77, v77, v78, s95
	v_max3_f32 v78, v100, v101, v102
	v_max3_f32 v79, v96, v97, v98
	v_max3_f32 v78, v78, v103, v99
	v_max3_f32 v77, v77, v78, v79
	v_mov_b32_e32 v78, v77
	s_nop 1
	v_permlane16_swap_b32_e32 v77, v78
	ds_read_b32 v76, v153 offset:37628
	v_max_f32_e32 v77, v77, v78
	v_mov_b32_e32 v78, v77
	s_nop 1
	v_permlane32_swap_b32_e32 v77, v78
	v_max_f32_e32 v77, v77, v78
	s_waitcnt lgkmcnt(0)
	v_fmamk_f32 v77, v77, 0x3e38aa3b, v76
	v_sub_f32_e32 v78, v77, v145
	v_cmp_ge_f32_e32 vcc, s97, v78
	v_max_f32_e32 v78, v145, v145
	v_max_f32_e32 v77, v78, v77
	s_cmp_lg_u64 vcc, exec
	v_sub_f32_e32 v78, v145, v77
	s_cselect_b64 s[6:7], -1, 0
	v_exp_f32_e32 v78, v78
	v_cndmask_b32_e64 v139, v145, v77, s[6:7]
	s_mov_b32 s100, 0x3e38aa3b
	v_sub_f32_e32 v170, v76, v139
	v_cndmask_b32_e64 v142, 1.0, v78, s[6:7]
	v_pk_fma_f32 v[76:77], v[108:109], s[100:101], v[170:171] op_sel_hi:[1,0,0]
	v_pk_fma_f32 v[78:79], v[110:111], s[100:101], v[170:171] op_sel_hi:[1,0,0]
	v_pk_fma_f32 v[80:81], v[104:105], s[100:101], v[170:171] op_sel_hi:[1,0,0]
	v_pk_fma_f32 v[82:83], v[106:107], s[100:101], v[170:171] op_sel_hi:[1,0,0]
	v_pk_fma_f32 v[88:89], v[100:101], s[100:101], v[170:171] op_sel_hi:[1,0,0]
	v_pk_fma_f32 v[90:91], v[102:103], s[100:101], v[170:171] op_sel_hi:[1,0,0]
	v_pk_fma_f32 v[92:93], v[96:97], s[100:101], v[170:171] op_sel_hi:[1,0,0]
	v_pk_fma_f32 v[94:95], v[98:99], s[100:101], v[170:171] op_sel_hi:[1,0,0]
	v_exp_f32_e32 v76, v76
	v_exp_f32_e32 v77, v77
	v_exp_f32_e32 v78, v78
	v_exp_f32_e32 v79, v79
	v_exp_f32_e32 v80, v80
	v_exp_f32_e32 v81, v81
	v_exp_f32_e32 v82, v82
	v_exp_f32_e32 v83, v83
	v_exp_f32_e32 v88, v88
	v_exp_f32_e32 v89, v89
	v_exp_f32_e32 v90, v90
	v_exp_f32_e32 v91, v91
	v_exp_f32_e32 v92, v92
	v_exp_f32_e32 v93, v93
	v_exp_f32_e32 v94, v94
	v_exp_f32_e32 v95, v95
	v_pk_add_f32 v[172:173], v[76:77], v[78:79]
	v_pk_add_f32 v[174:175], v[80:81], v[82:83]
	v_pk_add_f32 v[172:173], v[172:173], v[88:89]
	v_pk_add_f32 v[174:175], v[174:175], v[90:91]
	v_pk_add_f32 v[172:173], v[172:173], v[92:93]
	v_pk_add_f32 v[174:175], v[174:175], v[94:95]
	v_pk_add_f32 v[172:173], v[172:173], v[174:175]
	v_add_f32_e32 v147, v172, v173
	s_cbranch_execz .LBB0_1077

.LBB0_1064:
	s_andn2_b64 vcc, exec, s[4:5]
	s_mov_b64 s[6:7], -1
	s_cbranch_vccnz .LBB0_1078
	v_max3_f32 v97, v84, v85, v86
	v_max3_f32 v98, v72, v73, v74
	v_max3_f32 v97, v97, v87, v75
	v_max3_f32 v97, v97, v98, s95
	v_max3_f32 v98, v68, v69, v70
	v_max3_f32 v99, v64, v65, v66
	v_max3_f32 v98, v98, v71, v67
	v_max3_f32 v97, v97, v98, v99
	v_mov_b32_e32 v98, v97
	s_nop 1
	v_permlane16_swap_b32_e32 v97, v98
	ds_read_b32 v96, v153 offset:37628
	v_max_f32_e32 v97, v97, v98
	v_mov_b32_e32 v98, v97
	s_nop 1
	v_permlane32_swap_b32_e32 v97, v98
	v_max_f32_e32 v97, v97, v98
	s_waitcnt lgkmcnt(0)
	v_fmamk_f32 v97, v97, 0x3e38aa3b, v96
	v_sub_f32_e32 v98, v97, v146
	v_cmp_ge_f32_e32 vcc, s97, v98
	v_max_f32_e32 v98, v146, v146
	v_max_f32_e32 v97, v98, v97
	s_cmp_lg_u64 vcc, exec
	v_sub_f32_e32 v98, v146, v97
	s_cselect_b64 s[4:5], -1, 0
	v_exp_f32_e32 v98, v98
	v_cndmask_b32_e64 v137, v146, v97, s[4:5]
	s_mov_b32 s100, 0x3e38aa3b
	v_sub_f32_e32 v170, v96, v137
	v_cndmask_b32_e64 v142, 1.0, v98, s[4:5]
	v_pk_fma_f32 v[96:97], v[84:85], s[100:101], v[170:171] op_sel_hi:[1,0,0]
	v_pk_fma_f32 v[98:99], v[86:87], s[100:101], v[170:171] op_sel_hi:[1,0,0]
	v_pk_fma_f32 v[100:101], v[72:73], s[100:101], v[170:171] op_sel_hi:[1,0,0]
	v_pk_fma_f32 v[102:103], v[74:75], s[100:101], v[170:171] op_sel_hi:[1,0,0]
	v_pk_fma_f32 v[104:105], v[68:69], s[100:101], v[170:171] op_sel_hi:[1,0,0]
	v_pk_fma_f32 v[106:107], v[70:71], s[100:101], v[170:171] op_sel_hi:[1,0,0]
	v_pk_fma_f32 v[108:109], v[64:65], s[100:101], v[170:171] op_sel_hi:[1,0,0]
	v_pk_fma_f32 v[110:111], v[66:67], s[100:101], v[170:171] op_sel_hi:[1,0,0]
	v_exp_f32_e32 v96, v96
	v_exp_f32_e32 v97, v97
	v_exp_f32_e32 v98, v98
	v_exp_f32_e32 v99, v99
	v_exp_f32_e32 v100, v100
	v_exp_f32_e32 v101, v101
	v_exp_f32_e32 v102, v102
	v_exp_f32_e32 v103, v103
	v_exp_f32_e32 v104, v104
	v_exp_f32_e32 v105, v105
	v_exp_f32_e32 v106, v106
	v_exp_f32_e32 v107, v107
	v_exp_f32_e32 v108, v108
	v_exp_f32_e32 v109, v109
	v_exp_f32_e32 v110, v110
	v_exp_f32_e32 v111, v111
	v_pk_add_f32 v[172:173], v[96:97], v[98:99]
	v_pk_add_f32 v[174:175], v[100:101], v[102:103]
	v_pk_add_f32 v[172:173], v[172:173], v[104:105]
	v_pk_add_f32 v[174:175], v[174:175], v[106:107]
	v_pk_add_f32 v[172:173], v[172:173], v[108:109]
	v_pk_add_f32 v[174:175], v[174:175], v[110:111]
	v_pk_add_f32 v[172:173], v[172:173], v[174:175]
	v_add_f32_e32 v145, v172, v173
	s_cbranch_execz .LBB0_1079
